# attention phases (k1, k3): one static s_setprio 1 for waves 4-7 at phase entry, reset at phase end
# speedup vs baseline: 1.0068x; 1.0068x over previous
; __device__ __forceinline__ void phase_dil_combine(const PT a, int lane, int gw, int ngw) {
;     unsigned char* ws = a.ws(); const float* oag = (const float*)(ws + WS_OAG); const float* lseb = (const float*)(ws + WS_LSE); bf16* oa = (bf16*)(ws + WS_OA);
;     for (int tok = gw; tok < M; tok += ngw) {
;         const int h = lane >> 3;
;         const float l0 = lseb[((size_t)0 * M + tok) * 8 + h], l1 = lseb[((size_t)1 * M + tok) * 8 + h], l2 = lseb[((size_t)2 * M + tok) * 8 + h];
;         const float mx = fmaxf(l0, fmaxf(l1, l2)); float w0 = __expf(l0 - mx), w1 = __expf(l1 - mx), w2 = __expf(l2 - mx); const float iw = 1.0f / (w0 + w1 + w2); w0 *= iw; w1 *= iw; w2 *= iw;
;         const f32x4* p0 = (const f32x4*)(oag + ((size_t)0 * M + tok) * 512 + lane * 8); const f32x4* p1 = (const f32x4*)(oag + ((size_t)1 * M + tok) * 512 + lane * 8); const f32x4* p2 = (const f32x4*)(oag + ((size_t)2 * M + tok) * 512 + lane * 8);
;         const f32x4 x0 = w0 * p0[0] + w1 * p1[0] + w2 * p2[0], x1 = w0 * p0[1] + w1 * p1[1] + w2 * p2[1];
; __global__ void __launch_bounds__(512, 2) mega_fwd(Args ka) {
;     ...
;             if (k == 1) {
;                 for (int rep = 0; rep < ((PROBE_SUB & 1) ? 2 : 1); ++rep) { asm volatile("" : "+v"(tid), "+s"(bid)); phase_compress_mfma(a, l, (unsigned char*)ldsf, tid, tid & 63, __builtin_amdgcn_readfirstlane(tid >> 6), bid, nblk); }
;                 for (int rep = 0; rep < ((PROBE_SUB & 2) ? 2 : 1); ++rep) { asm volatile("" : "+v"(tid), "+s"(bid)); phase_dilated_mfma(a, (unsigned char*)ldsf, tid, tid & 63, __builtin_amdgcn_readfirstlane(tid >> 6), bid, nblk); }
;                 for (int rep = 0; rep < ((PROBE_SUB & 4) ? 2 : 1); ++rep) { asm volatile("" : "+v"(tid), "+s"(bid)); phase_diff_mfma(a, l, (unsigned char*)ldsf, tid, tid & 63, __builtin_amdgcn_readfirstlane(tid >> 6), bid, nblk); } }
;             else if (k == 3) { phase_dil_combine(a, lane, gw, ngw); phase_nsa_mfma(a, (unsigned char*)ldsf, tid, lane, wave, bid, nblk); }
.LBB0_101:
	s_andn2_b64 vcc, exec, s[0:1]
	s_cbranch_vccnz .LBB0_384
	s_mov_b64 s[8:9], s[80:81]
	v_writelane_b32 v253, s73, 30
	s_mov_b32 s10, s82
	v_writelane_b32 v253, s8, 31
	s_add_i32 s73, s20, 0
	s_cmp_lt_i32 s27, 3
	v_writelane_b32 v253, s9, 32
	v_writelane_b32 v253, s10, 33
	v_writelane_b32 v253, s11, 34
	v_writelane_b32 v253, s30, 35
	s_mov_b64 s[0:1], -1
	s_nop 0
	v_writelane_b32 v253, s31, 36
	v_writelane_b32 v253, s58, 37
	s_cbranch_scc1 .LBB0_219
	s_cmp_eq_u32 s27, 3
	s_cbranch_scc0 .LBB0_218
	v_readfirstlane_b32 s0, v210
	s_nop 3
	s_cmp_ge_u32 s0, 0x100
	s_cbranch_scc0 .Lprio_skip_k3
	s_setprio 1
.Lprio_skip_k3:
	v_readlane_b32 s0, v253, 30
	s_cmpk_gt_i32 s4, 0x1fff
	s_nop 0
	v_mov_b32_e32 v0, s0
	ds_read_b64 v[2:3], v0 offset:176
	s_waitcnt lgkmcnt(0)
	v_readfirstlane_b32 s1, v3
	v_readfirstlane_b32 s0, v2
	s_cbranch_scc1 .LBB0_107
	s_ashr_i32 s5, s4, 31
	s_mul_i32 s8, s4, 0x1400
	s_mul_hi_i32 s7, s4, 0x1400
	s_add_u32 s8, s8, 0x23800000
	s_addc_u32 s7, s7, 0
	v_mov_b32_e32 v5, s7
	s_ashr_i32 s7, s6, 31
	s_lshl_b64 s[10:11], s[4:5], 11
	s_lshl_b64 s[12:13], s[4:5], 5
	v_lshrrev_b32_e32 v0, 1, v148
	v_lshl_or_b32 v4, v148, 4, s8
	s_mul_hi_i32 s9, s6, 0x1400
	s_mul_i32 s8, s6, 0x1400
	v_lshl_or_b32 v6, v148, 5, s10
	v_mov_b32_e32 v7, s11
	s_lshl_b64 s[10:11], s[6:7], 11
	v_and_or_b32 v8, v0, 28, s12
	v_mov_b32_e32 v9, s13
	s_lshl_b64 s[12:13], s[6:7], 5

;     __device__ __forceinline__ const float* in(int i) const { return (const float*)(const __attribute__((address_space(1))) float*)get(i); }
; __device__ __forceinline__ void phase_compress_mfma(const PT a, int lyr, unsigned char* ldsb, int tid, int lane, int wave, int bid, int nblk) {
;     unsigned char* ws = a.ws(); const bf16* proj = (const bf16*)(ws + WS_PROJ);
;     unsigned char* cw = ws + WS_CW + (size_t)lyr * 4 * MiB;
;     bf16* Ab = (bf16*)ldsb; float* RED = (float*)(ldsb + 17408);
;     const int l32 = lane & 31, hi = lane >> 5;
;     __syncthreads();
;     for (int u = bid; u < 64; u += nblk) {
;         const int kv = u >> 5, rg = u & 31;
;         const bf16* W1t = (const bf16*)(cw + (size_t)kv * MiB); const bf16* W2t = (const bf16*)(cw + 2 * MiB + (size_t)kv * 65536);
;         const float* pos = a.in(3 + kv) + (size_t)lyr * 2048; float* dst = (float*)(ws + (kv ? WS_VC : WS_KC));
;         f32x16 acc;
; #pragma unroll
;         for (int i = 0; i < 16; ++i) acc[i] = 0.f;
;         const bf16* wrow = W1t + (size_t)(32 * wave + l32) * 2048 + hi * 8;
; #pragma unroll 1
;         for (int kc = 0; kc < 8; ++kc) {
;             bf16x8 af[16];
; #pragma unroll
;             for (int kk = 0; kk < 16; ++kk) af[kk] = *(const bf16x8*)(wrow + kc * 256 + kk * 16);
;             __syncthreads();
; #pragma unroll
;             for (int r2 = 0; r2 < 2; ++r2) { const int idx = tid + 512 * r2, row = idx >> 5, ch = idx & 31; int r = rg * 32 + row; r = r < 1016 ? r : 1015;
; __global__ void __launch_bounds__(512, 2) mega_fwd(Args ka) {
;     ...
;             if (k == 1) {
;                 for (int rep = 0; rep < ((PROBE_SUB & 1) ? 2 : 1); ++rep) { asm volatile("" : "+v"(tid), "+s"(bid)); phase_compress_mfma(a, l, (unsigned char*)ldsf, tid, tid & 63, __builtin_amdgcn_readfirstlane(tid >> 6), bid, nblk); }
;                 for (int rep = 0; rep < ((PROBE_SUB & 2) ? 2 : 1); ++rep) { asm volatile("" : "+v"(tid), "+s"(bid)); phase_dilated_mfma(a, (unsigned char*)ldsf, tid, tid & 63, __builtin_amdgcn_readfirstlane(tid >> 6), bid, nblk); }
;                 for (int rep = 0; rep < ((PROBE_SUB & 4) ? 2 : 1); ++rep) { asm volatile("" : "+v"(tid), "+s"(bid)); phase_diff_mfma(a, l, (unsigned char*)ldsf, tid, tid & 63, __builtin_amdgcn_readfirstlane(tid >> 6), bid, nblk); } }
.LBB0_219:
	s_andn2_b64 vcc, exec, s[0:1]
	s_cbranch_vccnz .LBB0_383
	s_cmp_lg_u32 s27, 1
	s_cbranch_scc1 .LBB0_383
	v_readfirstlane_b32 s0, v210
	s_nop 3
	s_cmp_ge_u32 s0, 0x100
	s_cbranch_scc0 .Lprio_skip_k1
	s_setprio 1
.Lprio_skip_k1:
	v_readlane_b32 s0, v253, 30
	v_readlane_b32 s4, v253, 28
	s_mov_b32 s14, s4
	v_mov_b32_e32 v0, s0
	ds_read_b64 v[2:3], v0 offset:176
	v_readfirstlane_b32 s2, v146
	s_cmp_lt_i32 s4, 64
	s_waitcnt vmcnt(0) lgkmcnt(0)
	s_barrier
	v_readfirstlane_b32 s1, v3
	v_readfirstlane_b32 s0, v2
	s_cbranch_scc0 .LBB0_298
	s_lshl_b64 s[4:5], s[30:31], 13
	s_lshl_b64 s[6:7], s[30:31], 22
	s_add_u32 s10, s0, s6
	s_addc_u32 s11, s1, s7
	s_ashr_i32 s12, s2, 1
	s_and_b32 s8, s12, 0xffffffe0
	s_ashr_i32 s9, s8, 31
	s_lshl_b64 s[8:9], s[8:9], 1
	v_bfe_u32 v8, v146, 5, 1
	s_add_u32 s8, s10, s8
	v_lshlrev_b32_e32 v0, 3, v8
	s_addc_u32 s9, s11, s9
	v_and_b32_e32 v3, 31, v146
	v_lshl_add_u64 v[6:7], s[8:9], 0, v[0:1]
	s_mov_b64 s[8:9], 0x32600000
	s_and_b32 s2, s2, 0x3fffffc0
	v_mul_u32_u24_e32 v4, 0x210, v3
	v_lshlrev_b32_e32 v11, 4, v8
	v_lshl_add_u64 v[90:91], v[6:7], 0, s[8:9]
	v_lshl_or_b32 v7, v8, 2, s2
	v_and_b32_e32 v5, 63, v146
	v_lshl_add_u32 v10, v3, 4, s73
	v_add3_u32 v115, s73, v4, v11
	v_lshlrev_b32_e32 v4, 8, v3
	v_mul_lo_u32 v7, v7, s96
	v_lshlrev_b32_e32 v3, 2, v3
	v_lshlrev_b32_e32 v0, 2, v5
	v_add3_u32 v118, s73, v7, v3
	v_mul_u32_u24_e32 v3, 33, v5
	v_lshl_add_u64 v[92:93], s[0:1], 0, v[0:1]
	v_add_u32_e32 v0, 0x200, v146
	v_ashrrev_i32_e32 v119, 6, v146
	v_lshl_add_u32 v3, v3, 2, s73
	v_lshlrev_b32_e32 v5, 2, v119
	v_add_u32_e32 v7, 0x4400, v3
	v_ashrrev_i32_e32 v128, 6, v0
	v_ashrrev_i32_e32 v116, 5, v146
	s_movk_i32 s2, 0x210
	v_ashrrev_i32_e32 v117, 5, v0
	v_add_u32_e32 v120, v3, v5
	v_add_u32_e32 v121, v7, v5
	v_add_u32_e32 v5, 0x400, v146
	v_lshlrev_b32_e32 v0, 2, v128
	v_mul_lo_u32 v12, v116, s2
	v_mul_lo_u32 v13, v117, s2
	v_ashrrev_i32_e32 v122, 6, v5
	v_add_u32_e32 v129, v3, v0
	v_add_u32_e32 v130, v7, v0
	v_mov_b32_e32 v0, s12
	s_movk_i32 s2, 0xffe0
	v_lshlrev_b32_e32 v5, 2, v122
	v_bfi_b32 v8, s2, v0, v146
	v_add_u32_e32 v123, v3, v5
	v_add_u32_e32 v124, v7, v5
	v_add_u32_e32 v5, 0x600, v146
	v_ashrrev_i32_e32 v9, 31, v8
	v_ashrrev_i32_e32 v125, 6, v5
	v_lshlrev_b64 v[8:9], 12, v[8:9]
	v_lshlrev_b32_e32 v5, 2, v125
	v_lshl_add_u64 v[8:9], s[6:7], 0, v[8:9]
	v_bfe_u32 v114, v146, 3, 2
	v_lshlrev_b32_e32 v2, 3, v146
	v_add_u32_e32 v126, v3, v5
	v_or_b32_e32 v8, v8, v11
	v_and_b32_e32 v3, 7, v146
	v_and_b32_e32 v2, 56, v2
	v_or_b32_e32 v6, 0x2000, v4
	v_lshl_add_u64 v[8:9], s[0:1], 0, v[8:9]
	s_mov_b64 s[6:7], 0x32400100
	v_lshlrev_b32_e32 v0, 8, v114
	v_lshlrev_b32_e32 v3, 5, v3
	v_add_u32_e32 v127, v7, v5
	v_lshl_add_u64 v[94:95], v[8:9], 0, s[6:7]
	v_or3_b32 v96, s4, v0, v3
	v_mov_b32_e32 v97, s5
	v_lshlrev_b32_e32 v0, 1, v2
	v_add_u32_e32 v131, v10, v12
	v_add_u32_e32 v132, v10, v13
	v_lshlrev_b32_e32 v98, 1, v4
	v_lshlrev_b32_e32 v100, 1, v6
	s_mov_b32 s8, s14
	s_branch .LBB0_224

; #define LAS __attribute__((address_space(3)))
; __device__ __forceinline__ unsigned xb_ld(unsigned* p)              { return __hip_atomic_load(p, __ATOMIC_RELAXED, __HIP_MEMORY_SCOPE_AGENT); }
; __device__ __forceinline__ unsigned xb_xcc_id() { return (unsigned)__builtin_amdgcn_s_getreg((3 << 11) | 20) & 0xFu; }
; __device__ __forceinline__ void xcd_barrier_complete(unsigned* bar, unsigned x, unsigned& nloc, unsigned& nx) {
;     ...
;     for (;;) {
;         sum = 0u; cnt = 0u; mine = 0u;
; #pragma unroll
;         for (unsigned j = 0; j < 16; ++j) { const unsigned c = xb_ld(&bar[XB_XCNT(j)]); sum += c; cnt += (c > 0u) ? 1u : 0u; mine = (j == x) ? c : mine; }
; __device__ __forceinline__ void xcd_barrier(const XcdBarrier& b) {
;     asm volatile("s_waitcnt vmcnt(0)" ::: "memory");
;     __syncthreads();
;     if (threadIdx.x == 0) {
;         unsigned* bar = b.bar;
;         __builtin_amdgcn_s_waitcnt(0);
;         unsigned nloc = b.st[0], nx = b.st[1];
;         if (nloc == 0u) { xcd_barrier_complete(bar, b.x, nloc, nx); b.st[0] = nloc; b.st[1] = nx; }
; __global__ void __launch_bounds__(512, 2) mega_fwd(Args ka) {
;     ...
;         if (ph + 1 < ph_hi) { XcdBarrier xbar; xbar.bar = (unsigned*)(a.ws() + WS_BAR); xbar.x = xb_xcc_id(); xbar.st = (volatile LAS unsigned*)(ldsl + PTAB_OFF + 256); xcd_barrier(xbar); }
.LBB0_514:
	s_setprio 0
	s_add_i32 s80, s80, 1
	s_cmp_ge_i32 s80, s81
	s_cselect_b64 s[0:1], -1, 0
	s_and_b64 vcc, exec, s[0:1]
	s_mov_b32 s28, 0x3fb8aa3b
	s_cbranch_vccnz .LBB0_568
	v_mov_b32_e32 v0, s73
	ds_read_b64 v[2:3], v0 offset:176
	s_getreg_b32 s2, hwreg(HW_REG_XCC_ID, 0, 4)
	s_waitcnt vmcnt(0)
	s_waitcnt vmcnt(0) lgkmcnt(0)
	s_barrier
	v_readfirstlane_b32 s7, v3
	v_readfirstlane_b32 s6, v2
	s_mov_b64 s[4:5], exec
	v_readlane_b32 s8, v253, 2
	v_readlane_b32 s9, v253, 3
	s_and_b64 s[8:9], s[4:5], s[8:9]
	s_mov_b64 exec, s[8:9]
	s_cbranch_execz .LBB0_567
	v_readlane_b32 s8, v253, 11
	s_waitcnt vmcnt(0) expcnt(0) lgkmcnt(0)
	s_and_b32 s2, s2, 15
	v_mov_b32_e32 v0, s8
	ds_read_b32 v3, v0
	v_readlane_b32 s8, v253, 12
	s_waitcnt lgkmcnt(0)
	v_cmp_ne_u32_e32 vcc, 0, v3
	v_mov_b32_e32 v0, s8
	ds_read_b32 v0, v0
	s_cbranch_vccnz .LBB0_531
	s_add_u32 s8, s6, 0x32c00200
	s_addc_u32 s9, s7, 0
	s_add_u32 s10, s6, 0x32c00400
	s_addc_u32 s11, s7, 0
	s_add_u32 s12, s6, 0x32c00500
	s_addc_u32 s13, s7, 0
	s_add_u32 s14, s6, 0x32c00600
	s_addc_u32 s15, s7, 0
	s_add_u32 s16, s6, 0x32c00700
	s_addc_u32 s17, s7, 0
	s_add_u32 s18, s6, 0x32c00800
	s_addc_u32 s19, s7, 0
	s_add_u32 s20, s6, 0x32c00900
	s_addc_u32 s21, s7, 0
	s_add_u32 s22, s6, 0x32c00a00
	s_addc_u32 s23, s7, 0
	s_add_u32 s24, s6, 0x32c00b00
	s_addc_u32 s25, s7, 0
	s_add_u32 s26, s6, 0x32c00c00
	s_addc_u32 s27, s7, 0
	s_add_u32 s28, s6, 0x32c00d00
	s_addc_u32 s29, s7, 0
	s_add_u32 s30, s6, 0x32c00e00
	s_addc_u32 s31, s7, 0
	s_add_u32 s34, s6, 0x32c00f00
	s_addc_u32 s35, s7, 0
	s_add_u32 s36, s6, 0x32c01000
	s_addc_u32 s37, s7, 0
	s_add_u32 s38, s6, 0x32c01100
	s_addc_u32 s39, s7, 0
	s_add_u32 s40, s6, 0x32c01200
	s_addc_u32 s41, s7, 0
	s_add_u32 s42, s6, 0x32c01300
	s_addc_u32 s43, s7, 0
	s_mov_b32 s50, 1
	s_branch .LBB0_519
